# LayerNorm: gamma/beta staged in LDS once per workgroup, row loop reads them with ds_read (was 15 global loads per row each waited with vmcnt(0) behind the previous stores)
# speedup vs baseline: 1.0081x; 1.0081x over previous
.LBB0_877:
	s_cmp_lt_i32 s94, 8
	s_cselect_b64 s[0:1], -1, 0
	s_and_b64 s[2:3], s[0:1], s[2:3]
	s_andn2_b64 vcc, exec, s[2:3]
	s_cbranch_vccnz .LBB0_881
	s_lshl_b32 s2, s76, 3
	s_add_i32 s2, s78, s2
	s_cmpk_gt_i32 s2, 0x1fff
	s_cbranch_scc1 .LBB0_881
	v_mbcnt_lo_u32_b32 v1, -1, 0
	v_mbcnt_hi_u32_b32 v2, -1, v1
	v_and_b32_e32 v1, 64, v2
	v_readlane_b32 s4, v249, 34
	v_add_u32_e32 v3, 64, v1
	v_xor_b32_e32 v1, 1, v2
	v_readlane_b32 s16, v249, 16
	v_readlane_b32 s5, v249, 35
	v_cmp_lt_i32_e32 vcc, v1, v3
	v_xor_b32_e32 v4, 2, v2
	v_lshlrev_b32_e32 v74, 4, v178
	v_mov_b32_e32 v75, 0
	v_readlane_b32 s26, v249, 26
	v_readlane_b32 s27, v249, 27
	v_readlane_b32 s28, v249, 28
	v_readlane_b32 s29, v249, 29
	s_lshl_b32 s6, s4, 3
	v_cndmask_b32_e32 v1, v2, v1, vcc
	v_cmp_lt_i32_e32 vcc, v4, v3
	v_lshl_add_u64 v[76:77], s[26:27], 0, v[74:75]
	v_lshl_add_u64 v[78:79], s[28:29], 0, v[74:75]
	s_mov_b64 s[4:5], 0x1000
	v_cndmask_b32_e32 v4, v2, v4, vcc
	v_lshl_add_u64 v[80:81], v[76:77], 0, s[4:5]
	v_lshl_add_u64 v[82:83], v[78:79], 0, s[4:5]
	s_mov_b64 s[4:5], 0x1400
	v_lshlrev_b32_e32 v97, 2, v4
	v_xor_b32_e32 v4, 4, v2
	v_lshl_add_u64 v[84:85], v[76:77], 0, s[4:5]
	v_lshl_add_u64 v[86:87], v[78:79], 0, s[4:5]
	s_mov_b64 s[4:5], 0x1800
	v_cmp_lt_i32_e32 vcc, v4, v3
	v_lshl_add_u64 v[88:89], v[76:77], 0, s[4:5]
	v_lshl_add_u64 v[90:91], v[78:79], 0, s[4:5]
	s_mov_b64 s[4:5], 0x1c00
	v_cndmask_b32_e32 v4, v2, v4, vcc
	v_lshl_add_u64 v[92:93], v[76:77], 0, s[4:5]
	v_lshl_add_u64 v[94:95], v[78:79], 0, s[4:5]
	s_mov_b64 s[4:5], 0x2000
	v_lshlrev_b32_e32 v131, 2, v4
	v_xor_b32_e32 v4, 8, v2
	v_lshl_add_u64 v[98:99], v[76:77], 0, s[4:5]
	v_lshl_add_u64 v[100:101], v[78:79], 0, s[4:5]
	s_mov_b64 s[4:5], 0x2400
	v_cmp_lt_i32_e32 vcc, v4, v3
	v_lshl_add_u64 v[102:103], v[76:77], 0, s[4:5]
	v_lshl_add_u64 v[104:105], v[78:79], 0, s[4:5]
	s_mov_b64 s[4:5], 0x2800
	v_cndmask_b32_e32 v4, v2, v4, vcc
	v_lshl_add_u64 v[106:107], v[76:77], 0, s[4:5]
	v_lshl_add_u64 v[108:109], v[78:79], 0, s[4:5]
	s_mov_b64 s[4:5], 0x2c00
	v_lshlrev_b32_e32 v146, 2, v4
	v_xor_b32_e32 v4, 16, v2
	v_lshl_add_u64 v[110:111], v[76:77], 0, s[4:5]
	v_lshl_add_u64 v[112:113], v[78:79], 0, s[4:5]
	s_mov_b64 s[4:5], 0x3000
	v_cmp_lt_i32_e32 vcc, v4, v3
	v_lshl_add_u64 v[114:115], v[76:77], 0, s[4:5]
	v_lshl_add_u64 v[116:117], v[78:79], 0, s[4:5]
	s_mov_b64 s[4:5], 0x3400
	v_cndmask_b32_e32 v4, v2, v4, vcc
	v_lshl_add_u64 v[118:119], v[76:77], 0, s[4:5]
	v_lshl_add_u64 v[120:121], v[78:79], 0, s[4:5]
	s_mov_b64 s[4:5], 0x3800
	v_lshlrev_b32_e32 v147, 2, v4
	v_xor_b32_e32 v4, 32, v2
	v_lshl_add_u64 v[122:123], v[76:77], 0, s[4:5]
	v_lshl_add_u64 v[124:125], v[78:79], 0, s[4:5]
	s_mov_b64 s[4:5], 0x3c00
	v_cmp_lt_i32_e32 vcc, v4, v3
	v_lshl_add_u64 v[126:127], v[76:77], 0, s[4:5]
	v_lshl_add_u64 v[128:129], v[78:79], 0, s[4:5]
	s_mul_i32 s4, s78, 0x2400
	v_cndmask_b32_e32 v2, v2, v4, vcc
	v_and_b32_e32 v5, 3, v0
	s_add_i32 s8, s4, 0
	v_lshlrev_b32_e32 v148, 2, v2
	v_lshrrev_b32_e32 v2, 3, v178
	s_movk_i32 s3, 0x90
	v_lshlrev_b32_e32 v149, 4, v5
	v_lshlrev_b32_e32 v150, 7, v5
	v_mov_b32_e32 v5, s8
	s_add_u32 s10, s92, 0x5b800000
	v_mad_u32_u24 v2, v2, s3, v5
	s_addc_u32 s11, s93, 0
	s_ashr_i32 s3, s2, 31
	v_lshlrev_b32_e32 v3, 4, v0
	s_lshl_b64 s[4:5], s[2:3], 14
	v_readlane_b32 s17, v249, 17
	v_readlane_b32 s18, v249, 18
	v_readlane_b32 s19, v249, 19
	v_readlane_b32 s20, v249, 20
	v_readlane_b32 s21, v249, 21
	v_readlane_b32 s22, v249, 22
	v_readlane_b32 s23, v249, 23
	v_and_b32_e32 v3, 0x70, v3
	v_mul_u32_u24_e32 v4, 0x90, v178
	v_lshrrev_b32_e32 v96, 2, v178
	v_or_b32_e32 v132, s4, v74
	v_mov_b32_e32 v133, s5
	s_ashr_i32 s7, s6, 31
	s_lshl_b64 s[4:5], s[2:3], 13
	s_mov_b32 s9, 0
	v_lshlrev_b32_e32 v1, 2, v1
	v_readlane_b32 s30, v249, 30
	v_readlane_b32 s31, v249, 31
	v_or_b32_e32 v130, 16, v96
	s_lshl_b64 s[12:13], s[6:7], 14
	v_lshl_or_b32 v134, v178, 3, s4
	v_mov_b32_e32 v135, s5
	s_lshl_b64 s[14:15], s[6:7], 13
	s_mov_b32 s3, 0x53801000
	s_mov_b32 s7, 0x53802000
	s_mov_b32 s16, 0x53803000
	v_mov_b32_e32 v151, 0x3727c5ac
	s_mov_b32 s17, 0xf800000
	v_mov_b32_e32 v152, 0x260
	s_mov_b32 s18, 0xb000000
	v_add_u32_e32 v153, v2, v3
	s_movk_i32 s19, 0x1000
	v_add_u32_e32 v154, s8, v4
	s_movk_i32 s20, 0x3000
	s_mov_b32 s21, 0x5b802000
	s_movk_i32 s22, 0x2000
	s_mov_b32 s23, 0xb001000
	v_readlane_b32 s24, v249, 24
	v_readlane_b32 s25, v249, 25
	v_lshlrev_b32_e32 v208, 4, v0
	v_add_u32_e32 v209, 0x2000, v208
	global_load_dwordx4 v[212:215], v208, s[26:27]
	global_load_dwordx4 v[216:219], v209, s[26:27]
	global_load_dwordx4 v[220:223], v208, s[28:29]
	global_load_dwordx4 v[224:227], v209, s[28:29]
	v_add_u32_e32 v210, 0x12000, v208
	v_lshlrev_b32_e32 v228, 4, v178
	v_add_u32_e32 v228, 0x12000, v228
	s_waitcnt vmcnt(0)
	ds_write_b128 v210, v[212:215]
	ds_write_b128 v210, v[216:219] offset:8192
	ds_write_b128 v210, v[220:223] offset:16384
	ds_write_b128 v210, v[224:227] offset:24576
	s_waitcnt lgkmcnt(0)
	s_barrier
.LBB0_880:
	v_lshl_add_u64 v[18:19], s[92:93], 0, v[132:133]
	v_add_co_u32_e64 v6, s[4:5], s3, v18
	v_lshl_add_u64 v[2:3], s[92:93], 0, v[134:135]
	s_nop 0
	v_addc_co_u32_e64 v7, s[4:5], 0, v19, s[4:5]
	v_add_co_u32_e64 v30, s[4:5], s7, v18
	v_add_co_u32_e32 v20, vcc, 0x53800000, v18
	s_nop 0
	v_addc_co_u32_e64 v31, s[4:5], 0, v19, s[4:5]
	v_add_co_u32_e64 v32, s[4:5], s16, v18
	v_addc_co_u32_e32 v21, vcc, 0, v19, vcc
	s_nop 0
	v_addc_co_u32_e64 v33, s[4:5], 0, v19, s[4:5]
	v_add_co_u32_e64 v140, s[4:5], s18, v2
	ds_read_b128 v[22:25], v228
	ds_read_b128 v[26:29], v228 offset:16384
	v_addc_co_u32_e64 v141, s[4:5], 0, v3, s[4:5]
	v_add_co_u32_e64 v136, s[4:5], s23, v2
	v_lshl_add_u64 v[138:139], s[30:31], 0, v[132:133]
	s_nop 0
	v_addc_co_u32_e64 v137, s[4:5], 0, v3, s[4:5]
	global_load_dwordx4 v[14:17], v[30:31], off offset:-4096
	global_load_dwordx4 v[10:13], v[6:7], off offset:1024
	global_load_dwordx4 v[2:5], v[6:7], off offset:2048
	s_nop 0
	global_load_dwordx4 v[6:9], v[6:7], off offset:3072
	s_nop 0
	global_load_dwordx4 v[62:65], v[30:31], off
	global_load_dwordx4 v[58:61], v[30:31], off offset:1024
	global_load_dwordx4 v[54:57], v[30:31], off offset:2048
	global_load_dwordx4 v[50:53], v[30:31], off offset:3072
	global_load_dwordx4 v[46:49], v[32:33], off
	global_load_dwordx4 v[42:45], v[32:33], off offset:1024
	global_load_dwordx4 v[38:41], v[32:33], off offset:2048
	global_load_dwordx4 v[34:37], v[32:33], off offset:3072
	global_load_dwordx4 v[70:73], v[20:21], off
	global_load_dwordx4 v[66:69], v[20:21], off offset:1024
	s_nop 0
	global_load_dwordx4 v[30:33], v[20:21], off offset:2048
	s_nop 0
	global_load_dwordx4 v[18:21], v[20:21], off offset:3072
	s_lshl_b32 s25, s2, 2
	s_and_b32 s25, s25, 32
	s_and_b32 s24, s2, 15
	s_lshl_b32 s26, s24, 6
	s_lshl_b32 s24, s24, 3
	v_lshl_add_u64 v[132:133], v[132:133], 0, s[12:13]
	v_lshl_add_u64 v[134:135], v[134:135], 0, s[14:15]
	s_waitcnt vmcnt(0)
	s_waitcnt lgkmcnt(0)
	v_mov_b32_e32 v142, v15
	v_mov_b32_e32 v143, v16
	v_mov_b32_e32 v144, v14
	v_mov_b32_e32 v145, v17
	v_add_f32_e32 v156, v10, v11
	v_add_f32_e32 v158, v12, v13
	v_mov_b32_e32 v157, v4
	v_mov_b32_e32 v159, v5
	v_mov_b32_e32 v160, v7
	v_mov_b32_e32 v161, v8
	v_mov_b32_e32 v162, v6
	v_mov_b32_e32 v163, v9
	v_mov_b32_e32 v168, v55
	v_mov_b32_e32 v169, v56
	v_mov_b32_e32 v170, v54
	v_mov_b32_e32 v171, v57
	v_mov_b32_e32 v186, v71
	v_mov_b32_e32 v187, v72
	v_mov_b32_e32 v188, v70
	v_mov_b32_e32 v189, v73
	v_mov_b32_e32 v190, v67
	v_mov_b32_e32 v191, v68
	v_mov_b32_e32 v200, v66
	v_mov_b32_e32 v201, v69
	v_pk_add_f32 v[142:143], v[142:143], v[144:145]
	v_pk_add_f32 v[144:145], v[156:157], v[158:159]
	v_pk_add_f32 v[156:157], v[160:161], v[162:163]
	v_pk_add_f32 v[160:161], v[168:169], v[170:171]
	v_pk_add_f32 v[168:169], v[186:187], v[188:189]
	v_pk_add_f32 v[170:171], v[190:191], v[200:201]
	v_add_f32_e32 v74, v168, v169
	v_pk_add_f32 v[168:169], v[170:171], v[170:171] op_sel:[0,1] op_sel_hi:[1,0]
	v_add_f32_e32 v172, v50, v51
	v_add_f32_e32 v174, v52, v53
	v_mov_b32_e32 v173, v48
	v_mov_b32_e32 v175, v49
	v_add_f32_e32 v202, v30, v31
	v_add_f32_e32 v204, v32, v33
	v_mov_b32_e32 v207, v18
	v_mov_b32_e32 v203, v20
	v_mov_b32_e32 v205, v21
	v_add_f32_e32 v206, 0, v74
	v_mov_b32_e32 v169, v19
	v_pk_add_f32 v[162:163], v[172:173], v[174:175]
	v_pk_add_f32 v[172:173], v[202:203], v[204:205]
	v_pk_add_f32 v[168:169], v[206:207], v[168:169]
	v_pk_add_f32 v[142:143], v[142:143], v[142:143] op_sel:[0,1] op_sel_hi:[1,0]
	v_pk_add_f32 v[168:169], v[168:169], v[172:173]
	v_mov_b32_e32 v143, v3
	v_pk_add_f32 v[168:169], v[168:169], v[168:169] op_sel:[0,1] op_sel_hi:[1,0]
	v_pk_add_f32 v[156:157], v[156:157], v[156:157] op_sel:[0,1] op_sel_hi:[1,0]
	v_mov_b32_e32 v169, v2
	v_pk_add_f32 v[142:143], v[168:169], v[142:143]
	v_add_f32_e32 v164, v62, v63
	v_pk_add_f32 v[142:143], v[142:143], v[144:145]
	v_add_f32_e32 v166, v64, v65
	v_pk_add_f32 v[142:143], v[142:143], v[142:143] op_sel:[0,1] op_sel_hi:[1,0]
	v_mov_b32_e32 v165, v60
	v_mov_b32_e32 v167, v61
	v_mov_b32_e32 v157, v59
	v_mov_b32_e32 v143, v58
	v_pk_add_f32 v[158:159], v[164:165], v[166:167]
	v_pk_add_f32 v[142:143], v[142:143], v[156:157]
	v_pk_add_f32 v[160:161], v[160:161], v[160:161] op_sel:[0,1] op_sel_hi:[1,0]
	v_pk_add_f32 v[142:143], v[142:143], v[158:159]
	v_mov_b32_e32 v161, v47
	v_pk_add_f32 v[142:143], v[142:143], v[142:143] op_sel:[0,1] op_sel_hi:[1,0]
	v_mov_b32_e32 v176, v43
	v_mov_b32_e32 v143, v46
	v_mov_b32_e32 v177, v44
	v_mov_b32_e32 v180, v42
	v_mov_b32_e32 v181, v45
	v_pk_add_f32 v[142:143], v[142:143], v[160:161]
	v_pk_add_f32 v[164:165], v[176:177], v[180:181]
	v_pk_add_f32 v[142:143], v[142:143], v[162:163]
	v_pk_add_f32 v[164:165], v[164:165], v[164:165] op_sel:[0,1] op_sel_hi:[1,0]
	v_pk_add_f32 v[142:143], v[142:143], v[142:143] op_sel:[0,1] op_sel_hi:[1,0]
	v_add_f32_e32 v182, v38, v39
	v_add_f32_e32 v184, v40, v41
	v_mov_b32_e32 v183, v36
	v_mov_b32_e32 v185, v37
	v_mov_b32_e32 v165, v35
	v_mov_b32_e32 v143, v34
	v_pk_add_f32 v[166:167], v[182:183], v[184:185]
	v_pk_add_f32 v[142:143], v[142:143], v[164:165]
	s_nop 0
	v_pk_add_f32 v[142:143], v[142:143], v[166:167]
	s_nop 0
	v_add_f32_e32 v74, v142, v143
	ds_bpermute_b32 v142, v1, v74
	s_waitcnt lgkmcnt(0)
	v_add_f32_e32 v74, v74, v142
	ds_bpermute_b32 v142, v97, v74
	s_waitcnt lgkmcnt(0)
	v_add_f32_e32 v74, v74, v142
	ds_bpermute_b32 v142, v131, v74
	s_waitcnt lgkmcnt(0)
	v_add_f32_e32 v74, v74, v142
	ds_bpermute_b32 v142, v146, v74
	s_waitcnt lgkmcnt(0)
	v_add_f32_e32 v74, v74, v142
	ds_bpermute_b32 v142, v147, v74
	s_waitcnt lgkmcnt(0)
	v_add_f32_e32 v74, v74, v142
	ds_bpermute_b32 v142, v148, v74
	s_waitcnt lgkmcnt(0)
	v_add_f32_e32 v74, v74, v142
	v_fmamk_f32 v157, v74, 0xb9800000, v71
	v_fmamk_f32 v156, v74, 0xb9800000, v70
	v_fmamk_f32 v73, v74, 0xb9800000, v73
	v_fmac_f32_e32 v72, 0xb9800000, v74
	v_fmamk_f32 v67, v74, 0xb9800000, v67
	v_fmamk_f32 v66, v74, 0xb9800000, v66
	v_fmamk_f32 v69, v74, 0xb9800000, v69
	v_fmac_f32_e32 v68, 0xb9800000, v74
	v_fmamk_f32 v159, v74, 0xb9800000, v31
	v_fmamk_f32 v158, v74, 0xb9800000, v30
	v_fmamk_f32 v31, v74, 0xb9800000, v21
	v_fmamk_f32 v30, v74, 0xb9800000, v20
	v_fmamk_f32 v145, v74, 0xb9800000, v15
	v_fmamk_f32 v144, v74, 0xb9800000, v14
	v_fmamk_f32 v143, v74, 0xb9800000, v11
	v_fmamk_f32 v142, v74, 0xb9800000, v10
	v_fmamk_f32 v15, v74, 0xb9800000, v5
	v_fmamk_f32 v14, v74, 0xb9800000, v4
	v_fmamk_f32 v11, v74, 0xb9800000, v7
	v_fmamk_f32 v10, v74, 0xb9800000, v6
	v_fmamk_f32 v71, v74, 0xb9800000, v63
	v_fmamk_f32 v70, v74, 0xb9800000, v62
	v_fmamk_f32 v63, v74, 0xb9800000, v61
	v_fmamk_f32 v62, v74, 0xb9800000, v60
	v_fmamk_f32 v61, v74, 0xb9800000, v55
	v_fmamk_f32 v60, v74, 0xb9800000, v54
	v_fmamk_f32 v55, v74, 0xb9800000, v51
	v_fmamk_f32 v54, v74, 0xb9800000, v50
	v_fmamk_f32 v51, v74, 0xb9800000, v49
	v_fmamk_f32 v50, v74, 0xb9800000, v48
	v_fmamk_f32 v49, v74, 0xb9800000, v43
	v_fmamk_f32 v48, v74, 0xb9800000, v42
	v_pk_mul_f32 v[4:5], v[72:73], v[72:73]
	v_pk_mul_f32 v[6:7], v[156:157], v[156:157]
	v_pk_mul_f32 v[20:21], v[68:69], v[68:69]
	v_pk_mul_f32 v[42:43], v[66:67], v[66:67]
	v_fmac_f32_e32 v32, 0xb9800000, v74
	v_pk_mov_b32 v[204:205], v[6:7], v[4:5] op_sel:[1,0]
	v_mov_b32_e32 v7, v5
	v_pk_mov_b32 v[4:5], v[42:43], v[20:21] op_sel:[1,0]
	v_mov_b32_e32 v43, v21
	v_fmamk_f32 v33, v74, 0xb9800000, v33
	v_fmamk_f32 v19, v74, 0xb9800000, v19
	v_fmac_f32_e32 v18, 0xb9800000, v74
	v_fmamk_f32 v17, v74, 0xb9800000, v17
	v_fmac_f32_e32 v16, 0xb9800000, v74
	v_fmamk_f32 v13, v74, 0xb9800000, v13
	v_fmac_f32_e32 v12, 0xb9800000, v74
	v_fmamk_f32 v3, v74, 0xb9800000, v3
	v_fmac_f32_e32 v2, 0xb9800000, v74
	v_fmamk_f32 v9, v74, 0xb9800000, v9
	v_fmac_f32_e32 v8, 0xb9800000, v74
	v_fmamk_f32 v65, v74, 0xb9800000, v65
	v_fmac_f32_e32 v64, 0xb9800000, v74
	v_fmamk_f32 v59, v74, 0xb9800000, v59
	v_fmac_f32_e32 v58, 0xb9800000, v74
	v_fmamk_f32 v57, v74, 0xb9800000, v57
	v_fmac_f32_e32 v56, 0xb9800000, v74
	v_fmamk_f32 v53, v74, 0xb9800000, v53
	v_fmac_f32_e32 v52, 0xb9800000, v74
	v_fmamk_f32 v47, v74, 0xb9800000, v47
	v_fmac_f32_e32 v46, 0xb9800000, v74
	v_fmamk_f32 v45, v74, 0xb9800000, v45
	v_fmac_f32_e32 v44, 0xb9800000, v74
	v_fmamk_f32 v39, v74, 0xb9800000, v39
	v_fmamk_f32 v38, v74, 0xb9800000, v38
	v_fmamk_f32 v41, v74, 0xb9800000, v41
	v_fmac_f32_e32 v40, 0xb9800000, v74
	v_fmamk_f32 v37, v74, 0xb9800000, v37
	v_fmamk_f32 v36, v74, 0xb9800000, v36
	v_fmamk_f32 v35, v74, 0xb9800000, v35
	v_fmac_f32_e32 v34, 0xb9800000, v74
	v_mul_f32_e32 v74, v158, v158
	v_mul_f32_e32 v160, v32, v32
	v_pk_add_f32 v[6:7], v[204:205], v[6:7]
	v_pk_add_f32 v[4:5], v[4:5], v[42:43]
	v_pk_fma_f32 v[20:21], v[158:159], v[158:159], v[74:75] op_sel_hi:[1,1,0]
	v_pk_fma_f32 v[160:161], v[32:33], v[32:33], v[160:161] op_sel_hi:[1,1,0]
	v_pk_add_f32 v[6:7], v[6:7], v[6:7] op_sel_hi:[0,1]
	v_pk_add_f32 v[4:5], v[4:5], v[4:5] op_sel_hi:[0,1]
	v_pk_mul_f32 v[162:163], v[16:17], v[16:17]
	v_pk_mul_f32 v[164:165], v[144:145], v[144:145]
	v_mul_f32_e32 v20, v18, v18
	v_mul_f32_e32 v160, v19, v19
	v_mul_f32_e32 v6, v30, v30
	v_mul_f32_e32 v4, v31, v31
	v_pk_mov_b32 v[206:207], v[164:165], v[162:163] op_sel:[1,0]
	v_mov_b32_e32 v165, v163
	v_pk_add_f32 v[20:21], v[20:21], v[160:161]
	v_pk_add_f32 v[4:5], v[6:7], v[4:5]
	v_mul_f32_e32 v166, v142, v142
	v_mul_f32_e32 v168, v12, v12
	v_pk_add_f32 v[42:43], v[206:207], v[164:165]
	v_pk_add_f32 v[4:5], v[20:21], v[4:5]
	v_pk_fma_f32 v[162:163], v[142:143], v[142:143], v[166:167] op_sel_hi:[1,1,0]
	v_pk_fma_f32 v[166:167], v[12:13], v[12:13], v[168:169] op_sel_hi:[1,1,0]
	v_pk_add_f32 v[42:43], v[42:43], v[42:43] op_sel_hi:[0,1]
	v_pk_add_f32 v[4:5], v[4:5], v[4:5] op_sel_hi:[0,1]
	v_pk_mul_f32 v[170:171], v[8:9], v[8:9]
	v_pk_mul_f32 v[172:173], v[10:11], v[10:11]
	v_mul_f32_e32 v162, v2, v2
	v_mul_f32_e32 v166, v3, v3
	v_mul_f32_e32 v42, v14, v14
	v_mul_f32_e32 v4, v15, v15
	v_pk_mov_b32 v[168:169], v[172:173], v[170:171] op_sel:[1,0]
	v_mov_b32_e32 v173, v171
	v_pk_add_f32 v[160:161], v[162:163], v[166:167]
	v_pk_add_f32 v[4:5], v[42:43], v[4:5]
	v_mul_f32_e32 v174, v70, v70
	v_mul_f32_e32 v176, v64, v64
	v_pk_add_f32 v[164:165], v[168:169], v[172:173]
	v_pk_add_f32 v[4:5], v[160:161], v[4:5]
	v_pk_fma_f32 v[170:171], v[70:71], v[70:71], v[174:175] op_sel_hi:[1,1,0]
	v_pk_fma_f32 v[174:175], v[64:65], v[64:65], v[176:177] op_sel_hi:[1,1,0]
	v_pk_add_f32 v[162:163], v[164:165], v[164:165] op_sel_hi:[0,1]
	v_pk_add_f32 v[4:5], v[4:5], v[4:5] op_sel_hi:[0,1]
	v_pk_mul_f32 v[180:181], v[56:57], v[56:57]
	v_pk_mul_f32 v[182:183], v[60:61], v[60:61]
	v_mul_f32_e32 v170, v58, v58
	v_mul_f32_e32 v174, v59, v59
	v_mul_f32_e32 v162, v62, v62
	v_mul_f32_e32 v4, v63, v63
	v_pk_mov_b32 v[176:177], v[182:183], v[180:181] op_sel:[1,0]
	v_mov_b32_e32 v183, v181
	v_pk_add_f32 v[164:165], v[170:171], v[174:175]
	v_pk_add_f32 v[4:5], v[162:163], v[4:5]
	v_mul_f32_e32 v184, v54, v54
	v_mul_f32_e32 v186, v52, v52
	v_pk_add_f32 v[168:169], v[176:177], v[182:183]
	v_pk_add_f32 v[4:5], v[164:165], v[4:5]
	v_pk_fma_f32 v[180:181], v[54:55], v[54:55], v[184:185] op_sel_hi:[1,1,0]
	v_pk_fma_f32 v[184:185], v[52:53], v[52:53], v[186:187] op_sel_hi:[1,1,0]
	v_pk_add_f32 v[166:167], v[168:169], v[168:169] op_sel_hi:[0,1]
	v_pk_add_f32 v[4:5], v[4:5], v[4:5] op_sel_hi:[0,1]
	v_pk_mul_f32 v[188:189], v[44:45], v[44:45]
	v_pk_mul_f32 v[190:191], v[48:49], v[48:49]
	v_mul_f32_e32 v180, v46, v46
	v_mul_f32_e32 v184, v47, v47
	v_mul_f32_e32 v166, v50, v50
	v_mul_f32_e32 v4, v51, v51
	v_pk_mov_b32 v[186:187], v[190:191], v[188:189] op_sel:[1,0]
	v_mov_b32_e32 v191, v189
	v_pk_add_f32 v[168:169], v[180:181], v[184:185]
	v_pk_add_f32 v[4:5], v[166:167], v[4:5]
	v_mul_f32_e32 v200, v38, v38
	v_mul_f32_e32 v202, v40, v40
	v_pk_add_f32 v[172:173], v[186:187], v[190:191]
	v_pk_add_f32 v[4:5], v[168:169], v[4:5]
	v_pk_fma_f32 v[188:189], v[38:39], v[38:39], v[200:201] op_sel_hi:[1,1,0]
	v_pk_fma_f32 v[200:201], v[40:41], v[40:41], v[202:203] op_sel_hi:[1,1,0]
	v_pk_add_f32 v[170:171], v[172:173], v[172:173] op_sel_hi:[0,1]
	v_pk_add_f32 v[4:5], v[4:5], v[4:5] op_sel_hi:[0,1]
	v_mul_f32_e32 v188, v34, v34
	v_mul_f32_e32 v200, v35, v35
	v_mul_f32_e32 v170, v36, v36
	v_mul_f32_e32 v4, v37, v37
	v_pk_add_f32 v[172:173], v[188:189], v[200:201]
	v_pk_add_f32 v[4:5], v[170:171], v[4:5]
	s_nop 0
	v_pk_add_f32 v[4:5], v[172:173], v[4:5]
	s_nop 0
	v_add_f32_e32 v4, v4, v5
	ds_bpermute_b32 v5, v1, v4
	s_waitcnt lgkmcnt(0)
	v_add_f32_e32 v4, v4, v5
	ds_bpermute_b32 v5, v97, v4
	s_waitcnt lgkmcnt(0)
	v_add_f32_e32 v4, v4, v5
	ds_bpermute_b32 v5, v131, v4
	s_waitcnt lgkmcnt(0)
	v_add_f32_e32 v4, v4, v5
	ds_bpermute_b32 v5, v146, v4
	s_waitcnt lgkmcnt(0)
	v_add_f32_e32 v4, v4, v5
	ds_bpermute_b32 v5, v147, v4
	s_waitcnt lgkmcnt(0)
	v_add_f32_e32 v4, v4, v5
	ds_bpermute_b32 v5, v148, v4
	s_waitcnt lgkmcnt(0)
	v_add_f32_e32 v4, v4, v5
	v_fmamk_f32 v4, v4, 0x39800000, v151
	v_mul_f32_e32 v5, 0x4f800000, v4
	v_cmp_gt_f32_e32 vcc, s17, v4
	s_nop 1
	v_cndmask_b32_e32 v4, v4, v5, vcc
	v_sqrt_f32_e32 v5, v4
	s_nop 0
	v_add_u32_e32 v6, -1, v5
	v_add_u32_e32 v7, 1, v5
	v_fma_f32 v20, -v6, v5, v4
	v_fma_f32 v21, -v7, v5, v4
	v_cmp_ge_f32_e64 s[4:5], 0, v20
	s_nop 1
	v_cndmask_b32_e64 v5, v5, v6, s[4:5]
	v_cmp_lt_f32_e64 s[4:5], 0, v21
	s_nop 1
	v_cndmask_b32_e64 v5, v5, v7, s[4:5]
	v_mul_f32_e32 v6, 0x37800000, v5
	v_cndmask_b32_e32 v5, v5, v6, vcc
	v_cmp_class_f32_e32 vcc, v4, v152
	s_nop 1
	v_cndmask_b32_e32 v4, v5, v4, vcc
	v_div_scale_f32 v5, s[4:5], v4, v4, 1.0
	v_rcp_f32_e32 v7, v5
	v_div_scale_f32 v6, vcc, 1.0, v4, 1.0
	s_ashr_i32 s4, s2, 7
	v_fma_f32 v20, -v5, v7, 1.0
	v_fmac_f32_e32 v7, v20, v7
	v_mul_f32_e32 v20, v6, v7
	v_fma_f32 v21, -v5, v20, v6
	v_fmac_f32_e32 v20, v21, v7
	v_fma_f32 v5, -v5, v20, v6
	v_div_fmas_f32 v5, v5, v7, v20
	v_div_fixup_f32 v42, v5, v4, 1.0
	v_pk_mul_f32 v[4:5], v[156:157], v[42:43] op_sel_hi:[1,0]
	v_pk_mul_f32 v[6:7], v[72:73], v[42:43] op_sel_hi:[1,0]
	v_pk_fma_f32 v[4:5], v[22:23], v[4:5], v[26:27]
	v_pk_fma_f32 v[6:7], v[24:25], v[6:7], v[28:29]
	v_cvt_pk_bf16_f32 v20, v4, v5
	v_cvt_pk_bf16_f32 v21, v6, v7
	global_store_dwordx4 v[138:139], v[4:7], off
	global_store_dwordx2 v[136:137], v[20:21], off offset:-4096
	ds_read_b128 v[20:23], v228 offset:1024
	s_nop 0
	ds_read_b128 v[24:27], v228 offset:17408
	v_pk_mul_f32 v[68:69], v[68:69], v[42:43] op_sel_hi:[1,0]
	v_pk_mul_f32 v[66:67], v[66:67], v[42:43] op_sel_hi:[1,0]
	v_pk_mul_f32 v[28:29], v[32:33], v[42:43] op_sel_hi:[1,0]
	v_pk_mul_f32 v[32:33], v[158:159], v[42:43] op_sel_hi:[1,0]
	v_pk_mul_f32 v[30:31], v[30:31], v[42:43] op_sel_hi:[1,0]
	v_pk_mul_f32 v[18:19], v[18:19], v[42:43] op_sel_hi:[1,0]
	v_add_co_u32_e32 v164, vcc, s22, v138
	s_bfe_u32 s5, s2, 0x30004
	s_nop 0
	v_addc_co_u32_e32 v165, vcc, 0, v139, vcc
	s_lshl_b32 s4, s4, 5
	s_lshl_b32 s8, s5, 10
	s_lshl_b32 s5, s5, 9
	v_or_b32_e32 v155, s4, v96
	s_or_b32 s5, s5, s24
	v_pk_add_f32 v[6:7], v[6:7], v[6:7]
	v_pk_add_f32 v[4:5], v[4:5], v[4:5]
	v_mov_b64_e32 v[72:73], s[92:93]
	s_add_i32 s2, s2, s6
	s_cmpk_lt_i32 s2, 0x2000
	s_waitcnt lgkmcnt(0)
	v_pk_fma_f32 v[20:21], v[20:21], v[66:67], v[24:25]
	v_pk_fma_f32 v[22:23], v[22:23], v[68:69], v[26:27]
	v_cvt_pk_bf16_f32 v24, v20, v21
	v_cvt_pk_bf16_f32 v25, v22, v23
	global_store_dwordx4 v[138:139], v[20:23], off offset:1024
	global_store_dwordx2 v[140:141], v[24:25], off offset:512
	ds_read_b128 v[24:27], v228 offset:2048
	s_nop 0
	ds_read_b128 v[66:69], v228 offset:18432
	s_waitcnt lgkmcnt(0)
	v_pk_fma_f32 v[24:25], v[24:25], v[32:33], v[66:67]
	v_pk_fma_f32 v[26:27], v[26:27], v[28:29], v[68:69]
	v_cvt_pk_bf16_f32 v28, v24, v25
	v_cvt_pk_bf16_f32 v29, v26, v27
	global_store_dwordx4 v[138:139], v[24:27], off offset:2048
	global_store_dwordx2 v[140:141], v[28:29], off offset:1024
	ds_read_b128 v[66:69], v228 offset:3072
	ds_read_b128 v[156:159], v228 offset:19456
	s_waitcnt lgkmcnt(0)
	v_pk_fma_f32 v[28:29], v[66:67], v[18:19], v[156:157]
	v_pk_fma_f32 v[30:31], v[68:69], v[30:31], v[158:159]
	v_cvt_pk_bf16_f32 v18, v28, v29
	v_cvt_pk_bf16_f32 v19, v30, v31
	global_store_dwordx4 v[138:139], v[28:31], off offset:3072
	global_store_dwordx2 v[140:141], v[18:19], off offset:1536
	ds_read_b128 v[156:159], v228 offset:4096
	ds_read_b128 v[160:163], v228 offset:20480
	v_pk_mul_f32 v[18:19], v[16:17], v[42:43] op_sel_hi:[1,0]
	v_pk_mul_f32 v[16:17], v[144:145], v[42:43] op_sel_hi:[1,0]
	v_mov_b32_e32 v43, s25
	v_pk_mul_f32 v[12:13], v[12:13], v[42:43] op_sel_hi:[1,0]
	v_pk_mul_f32 v[142:143], v[142:143], v[42:43] op_sel_hi:[1,0]
	v_mov_b64_e32 v[68:69], s[10:11]
	v_bitop3_b32 v74, s26, v43, v149 bitop3:0x36
	v_pk_mul_f32 v[14:15], v[14:15], v[42:43] op_sel_hi:[1,0]
	v_pk_mul_f32 v[2:3], v[2:3], v[42:43] op_sel_hi:[1,0]
	v_pk_mul_f32 v[8:9], v[8:9], v[42:43] op_sel_hi:[1,0]
	v_pk_mul_f32 v[10:11], v[10:11], v[42:43] op_sel_hi:[1,0]
	v_mov_b32_e32 v67, v75
	v_or_b32_e32 v66, s5, v150
	v_mad_i64_i32 v[166:167], s[24:25], v155, s20, v[72:73]
	v_lshl_add_u64 v[166:167], v[166:167], 0, v[66:67]
	v_pk_mul_f32 v[40:41], v[40:41], v[42:43] op_sel_hi:[1,0]
	v_pk_mul_f32 v[38:39], v[38:39], v[42:43] op_sel_hi:[1,0]
	s_waitcnt lgkmcnt(0)
	v_pk_fma_f32 v[16:17], v[156:157], v[16:17], v[160:161]
	v_pk_fma_f32 v[18:19], v[158:159], v[18:19], v[162:163]
	v_cvt_pk_bf16_f32 v32, v16, v17
	v_cvt_pk_bf16_f32 v33, v18, v19
	global_store_dwordx4 v[164:165], v[16:19], off offset:-4096
	global_store_dwordx2 v[140:141], v[32:33], off offset:2048
	ds_read_b128 v[156:159], v228 offset:5120
	ds_read_b128 v[160:163], v228 offset:21504
	v_add_co_u32_e32 v32, vcc, s19, v138
	s_waitcnt lgkmcnt(0)
	v_pk_fma_f32 v[142:143], v[156:157], v[142:143], v[160:161]
	v_pk_fma_f32 v[144:145], v[158:159], v[12:13], v[162:163]
	v_addc_co_u32_e32 v33, vcc, 0, v139, vcc
	v_cvt_pk_bf16_f32 v12, v142, v143
	v_cvt_pk_bf16_f32 v13, v144, v145
	global_store_dwordx4 v[32:33], v[142:145], off offset:1024
	global_store_dwordx2 v[140:141], v[12:13], off offset:2560
	ds_read_b128 v[156:159], v228 offset:6144
	ds_read_b128 v[160:163], v228 offset:22528
	v_mad_i64_i32 v[12:13], s[24:25], v155, s20, v[68:69]
	v_lshl_add_u64 v[12:13], v[12:13], 0, s[8:9]
	v_lshl_add_u64 v[168:169], v[12:13], 0, v[74:75]
	v_add_co_u32_e32 v166, vcc, s21, v166
	s_waitcnt lgkmcnt(0)
	v_pk_fma_f32 v[12:13], v[156:157], v[2:3], v[160:161]
	v_pk_fma_f32 v[14:15], v[158:159], v[14:15], v[162:163]
	v_cvt_pk_bf16_f32 v2, v12, v13
	v_cvt_pk_bf16_f32 v3, v14, v15
	global_store_dwordx4 v[32:33], v[12:15], off offset:2048
	global_store_dwordx2 v[140:141], v[2:3], off offset:3072
	ds_read_b128 v[156:159], v228 offset:7168
	ds_read_b128 v[160:163], v228 offset:23552
	ds_write_b128 v153, v[4:7]
	v_pk_add_f32 v[2:3], v[20:21], v[20:21]
	v_pk_add_f32 v[4:5], v[22:23], v[22:23]
	ds_write_b128 v153, v[2:5] offset:1152
	v_pk_add_f32 v[2:3], v[24:25], v[24:25]
	v_pk_add_f32 v[4:5], v[26:27], v[26:27]
	ds_write_b128 v153, v[2:5] offset:2304
	v_pk_add_f32 v[2:3], v[28:29], v[28:29]
	v_pk_add_f32 v[4:5], v[30:31], v[30:31]
	ds_write_b128 v153, v[2:5] offset:3456
	v_pk_add_f32 v[2:3], v[16:17], v[16:17]
	v_pk_add_f32 v[4:5], v[18:19], v[18:19]
	ds_write_b128 v153, v[2:5] offset:4608
	v_pk_add_f32 v[2:3], v[142:143], v[142:143]
	v_pk_add_f32 v[4:5], v[144:145], v[144:145]
	ds_write_b128 v153, v[2:5] offset:5760
	v_pk_add_f32 v[2:3], v[12:13], v[12:13]
	v_pk_add_f32 v[4:5], v[14:15], v[14:15]
	ds_write_b128 v153, v[2:5] offset:6912
	v_addc_co_u32_e32 v167, vcc, 0, v167, vcc
	s_waitcnt lgkmcnt(0)
	v_pk_fma_f32 v[2:3], v[10:11], v[156:157], v[160:161]
	v_pk_fma_f32 v[4:5], v[8:9], v[158:159], v[162:163]
	global_store_dwordx4 v[32:33], v[2:5], off offset:3072
	v_cvt_pk_bf16_f32 v6, v2, v3
	v_cvt_pk_bf16_f32 v7, v4, v5
	v_pk_add_f32 v[2:3], v[2:3], v[2:3]
	v_pk_add_f32 v[4:5], v[4:5], v[4:5]
	global_store_dwordx2 v[140:141], v[6:7], off offset:3584
	ds_write_b128 v153, v[2:5] offset:8064
	s_waitcnt lgkmcnt(0)
	ds_read_b128 v[2:5], v154
	ds_read_b128 v[6:9], v154 offset:16
	ds_read_b128 v[10:13], v154 offset:32
	ds_read_b128 v[14:17], v154 offset:48
	ds_read_b128 v[18:21], v154 offset:64
	ds_read_b128 v[22:25], v154 offset:80
	ds_read_b128 v[26:29], v154 offset:96
	ds_read_b128 v[30:33], v154 offset:112
	s_waitcnt lgkmcnt(0)
	v_cvt_scalef32_2xpk16_fp6_f32 v[2:7], v[2:17], v[18:33], 1.0
	global_store_dwordx4 v[168:169], v[2:5], off
	global_store_dwordx2 v[166:167], v[6:7], off
	s_waitcnt lgkmcnt(0)
	ds_read_b128 v[2:5], v228 offset:8192
	ds_read_b128 v[6:9], v228 offset:24576
	v_pk_mul_f32 v[10:11], v[64:65], v[42:43] op_sel_hi:[1,0]
	v_pk_mul_f32 v[12:13], v[70:71], v[42:43] op_sel_hi:[1,0]
	v_pk_mul_f32 v[14:15], v[62:63], v[42:43] op_sel_hi:[1,0]
	v_pk_mul_f32 v[16:17], v[58:59], v[42:43] op_sel_hi:[1,0]
	v_pk_mul_f32 v[18:19], v[56:57], v[42:43] op_sel_hi:[1,0]
	v_pk_mul_f32 v[20:21], v[60:61], v[42:43] op_sel_hi:[1,0]
	v_pk_mul_f32 v[22:23], v[52:53], v[42:43] op_sel_hi:[1,0]
	v_pk_mul_f32 v[24:25], v[54:55], v[42:43] op_sel_hi:[1,0]
	v_pk_mul_f32 v[26:27], v[50:51], v[42:43] op_sel_hi:[1,0]
	v_pk_mul_f32 v[28:29], v[46:47], v[42:43] op_sel_hi:[1,0]
	v_add_co_u32_e32 v52, vcc, s20, v138
	v_pk_mul_f32 v[30:31], v[44:45], v[42:43] op_sel_hi:[1,0]
	s_nop 0
	v_addc_co_u32_e32 v53, vcc, 0, v139, vcc
	v_pk_mul_f32 v[32:33], v[48:49], v[42:43] op_sel_hi:[1,0]
	v_or_b32_e32 v43, s4, v130
	v_pk_mul_f32 v[36:37], v[36:37], v[42:43] op_sel_hi:[1,0]
	v_pk_mul_f32 v[34:35], v[34:35], v[42:43] op_sel_hi:[1,0]
	v_mad_i64_i32 v[44:45], s[4:5], v43, s20, v[68:69]
	v_mad_i64_i32 v[46:47], s[4:5], v43, s20, v[72:73]
	v_lshl_add_u64 v[44:45], v[44:45], 0, s[8:9]
	v_lshl_add_u64 v[46:47], v[46:47], 0, v[66:67]
	v_lshl_add_u64 v[44:45], v[44:45], 0, v[74:75]
	v_add_co_u32_e32 v46, vcc, 0x5b802000, v46
	s_waitcnt lgkmcnt(0)
	v_pk_fma_f32 v[2:3], v[12:13], v[2:3], v[6:7]
	v_pk_fma_f32 v[4:5], v[10:11], v[4:5], v[8:9]
	v_cvt_pk_bf16_f32 v6, v2, v3
	v_cvt_pk_bf16_f32 v7, v4, v5
	global_store_dwordx4 v[164:165], v[2:5], off
	global_store_dwordx2 v[136:137], v[6:7], off
	ds_read_b128 v[6:9], v228 offset:9216
	s_nop 0
	ds_read_b128 v[10:13], v228 offset:25600
	v_pk_add_f32 v[2:3], v[2:3], v[2:3]
	v_pk_add_f32 v[4:5], v[4:5], v[4:5]
	v_addc_co_u32_e32 v47, vcc, 0, v47, vcc
	s_waitcnt lgkmcnt(0)
	v_pk_fma_f32 v[6:7], v[16:17], v[6:7], v[10:11]
	v_pk_fma_f32 v[8:9], v[14:15], v[8:9], v[12:13]
	v_cvt_pk_bf16_f32 v10, v6, v7
	v_cvt_pk_bf16_f32 v11, v8, v9
	global_store_dwordx4 v[164:165], v[6:9], off offset:1024
	global_store_dwordx2 v[136:137], v[10:11], off offset:512
	ds_read_b128 v[10:13], v228 offset:10240
	s_nop 0
	ds_read_b128 v[14:17], v228 offset:26624
	s_waitcnt lgkmcnt(0)
	v_pk_fma_f32 v[10:11], v[20:21], v[10:11], v[14:15]
	v_pk_fma_f32 v[12:13], v[18:19], v[12:13], v[16:17]
	v_cvt_pk_bf16_f32 v14, v10, v11
	v_cvt_pk_bf16_f32 v15, v12, v13
	global_store_dwordx4 v[164:165], v[10:13], off offset:2048
	global_store_dwordx2 v[136:137], v[14:15], off offset:1024
	ds_read_b128 v[14:17], v228 offset:11264
	s_nop 0
	ds_read_b128 v[18:21], v228 offset:27648
	s_waitcnt lgkmcnt(0)
	v_pk_fma_f32 v[14:15], v[24:25], v[14:15], v[18:19]
	v_pk_fma_f32 v[16:17], v[22:23], v[16:17], v[20:21]
	v_cvt_pk_bf16_f32 v18, v14, v15
	v_cvt_pk_bf16_f32 v19, v16, v17
	global_store_dwordx4 v[164:165], v[14:17], off offset:3072
	global_store_dwordx2 v[136:137], v[18:19], off offset:1536
	ds_read_b128 v[18:21], v228 offset:12288
	s_nop 0
	ds_read_b128 v[22:25], v228 offset:28672
	s_waitcnt lgkmcnt(0)
	v_pk_fma_f32 v[18:19], v[28:29], v[18:19], v[22:23]
	v_pk_fma_f32 v[20:21], v[26:27], v[20:21], v[24:25]
	v_cvt_pk_bf16_f32 v22, v18, v19
	v_cvt_pk_bf16_f32 v23, v20, v21
	global_store_dwordx4 v[52:53], v[18:21], off
	global_store_dwordx2 v[136:137], v[22:23], off offset:2048
	ds_read_b128 v[22:25], v228 offset:13312
	s_nop 0
	ds_read_b128 v[26:29], v228 offset:29696
	s_waitcnt lgkmcnt(0)
	v_pk_fma_f32 v[22:23], v[32:33], v[22:23], v[26:27]
	v_pk_fma_f32 v[24:25], v[30:31], v[24:25], v[28:29]
	v_cvt_pk_bf16_f32 v26, v22, v23
	v_cvt_pk_bf16_f32 v27, v24, v25
	global_store_dwordx4 v[52:53], v[22:25], off offset:1024
	global_store_dwordx2 v[136:137], v[26:27], off offset:2560
	ds_read_b128 v[26:29], v228 offset:14336
	s_nop 0
	ds_read_b128 v[30:33], v228 offset:30720
	s_waitcnt lgkmcnt(0)
	v_pk_fma_f32 v[26:27], v[38:39], v[26:27], v[30:31]
	v_pk_fma_f32 v[28:29], v[40:41], v[28:29], v[32:33]
	v_cvt_pk_bf16_f32 v30, v26, v27
	v_cvt_pk_bf16_f32 v31, v28, v29
	global_store_dwordx4 v[52:53], v[26:29], off offset:2048
	global_store_dwordx2 v[136:137], v[30:31], off offset:3072
	ds_read_b128 v[30:33], v228 offset:15360
	s_nop 0
	ds_read_b128 v[38:41], v228 offset:31744
	ds_write_b128 v153, v[2:5]
	v_pk_add_f32 v[2:3], v[6:7], v[6:7]
	v_pk_add_f32 v[4:5], v[8:9], v[8:9]
	ds_write_b128 v153, v[2:5] offset:1152
	v_pk_add_f32 v[2:3], v[10:11], v[10:11]
	v_pk_add_f32 v[4:5], v[12:13], v[12:13]
	ds_write_b128 v153, v[2:5] offset:2304
	v_pk_add_f32 v[2:3], v[14:15], v[14:15]
	v_pk_add_f32 v[4:5], v[16:17], v[16:17]
	ds_write_b128 v153, v[2:5] offset:3456
	v_pk_add_f32 v[2:3], v[18:19], v[18:19]
	v_pk_add_f32 v[4:5], v[20:21], v[20:21]
	ds_write_b128 v153, v[2:5] offset:4608
	v_pk_add_f32 v[2:3], v[22:23], v[22:23]
	v_pk_add_f32 v[4:5], v[24:25], v[24:25]
	ds_write_b128 v153, v[2:5] offset:5760
	v_pk_add_f32 v[2:3], v[26:27], v[26:27]
	v_pk_add_f32 v[4:5], v[28:29], v[28:29]
	ds_write_b128 v153, v[2:5] offset:6912
	s_waitcnt lgkmcnt(0)
	v_pk_fma_f32 v[2:3], v[34:35], v[30:31], v[38:39]
	v_pk_fma_f32 v[4:5], v[36:37], v[32:33], v[40:41]
	global_store_dwordx4 v[52:53], v[2:5], off offset:3072
	v_cvt_pk_bf16_f32 v6, v2, v3
	v_cvt_pk_bf16_f32 v7, v4, v5
	v_pk_add_f32 v[2:3], v[2:3], v[2:3]
	v_pk_add_f32 v[4:5], v[4:5], v[4:5]
	global_store_dwordx2 v[136:137], v[6:7], off offset:3584
	ds_write_b128 v153, v[2:5] offset:8064
	s_waitcnt lgkmcnt(0)
	ds_read_b128 v[2:5], v154
	ds_read_b128 v[6:9], v154 offset:16
	ds_read_b128 v[10:13], v154 offset:32
	ds_read_b128 v[14:17], v154 offset:48
	ds_read_b128 v[18:21], v154 offset:64
	ds_read_b128 v[22:25], v154 offset:80
	ds_read_b128 v[26:29], v154 offset:96
	ds_read_b128 v[30:33], v154 offset:112
	s_waitcnt lgkmcnt(0)
	v_cvt_scalef32_2xpk16_fp6_f32 v[2:7], v[2:17], v[18:33], 1.0
	global_store_dwordx4 v[44:45], v[2:5], off
	global_store_dwordx2 v[46:47], v[6:7], off
	s_waitcnt lgkmcnt(0)
	s_cbranch_scc1 .LBB0_880

.LBB0_1660:
	s_cmp_lt_i32 s94, 15
	s_cselect_b64 s[2:3], -1, 0
	s_and_b64 s[0:1], s[2:3], s[0:1]
	s_andn2_b64 vcc, exec, s[0:1]
	s_cbranch_vccnz .LBB0_1664
	s_lshl_b32 s0, s76, 3
	s_add_i32 s4, s78, s0
	s_cmpk_gt_i32 s4, 0x1fff
	s_cbranch_scc1 .LBB0_1664
	v_mbcnt_lo_u32_b32 v1, -1, 0
	v_mbcnt_hi_u32_b32 v2, -1, v1
	v_and_b32_e32 v1, 64, v2
	v_add_u32_e32 v3, 64, v1
	v_xor_b32_e32 v1, 1, v2
	v_cmp_lt_i32_e32 vcc, v1, v3
	v_xor_b32_e32 v4, 2, v2
	v_readlane_b32 s8, v249, 16
	v_cndmask_b32_e32 v1, v2, v1, vcc
	v_cmp_lt_i32_e32 vcc, v4, v3
	v_readlane_b32 s0, v249, 34
	v_readlane_b32 s10, v249, 18
	v_cndmask_b32_e32 v4, v2, v4, vcc
	v_lshlrev_b32_e32 v130, 2, v4
	v_xor_b32_e32 v4, 4, v2
	v_cmp_lt_i32_e32 vcc, v4, v3
	v_readlane_b32 s11, v249, 19
	v_readlane_b32 s12, v249, 20
	v_cndmask_b32_e32 v4, v2, v4, vcc
	v_lshlrev_b32_e32 v131, 2, v4
	v_xor_b32_e32 v4, 8, v2
	v_cmp_lt_i32_e32 vcc, v4, v3
	v_readlane_b32 s13, v249, 21
	v_readlane_b32 s14, v249, 22
	v_cndmask_b32_e32 v4, v2, v4, vcc
	v_lshlrev_b32_e32 v132, 2, v4
	v_xor_b32_e32 v4, 16, v2
	v_cmp_lt_i32_e32 vcc, v4, v3
	v_readlane_b32 s15, v249, 23
	v_readlane_b32 s18, v249, 26
	v_cndmask_b32_e32 v4, v2, v4, vcc
	v_lshlrev_b32_e32 v133, 2, v4
	v_xor_b32_e32 v4, 32, v2
	v_cmp_lt_i32_e32 vcc, v4, v3
	v_readlane_b32 s19, v249, 27
	v_readlane_b32 s20, v249, 28
	v_readlane_b32 s21, v249, 29
	v_readlane_b32 s1, v249, 35
	v_cndmask_b32_e32 v2, v2, v4, vcc
	v_lshlrev_b32_e32 v74, 4, v178
	v_mov_b32_e32 v75, 0
	v_readlane_b32 s22, v249, 30
	v_readlane_b32 s23, v249, 31
	s_mov_b64 s[12:13], s[20:21]
	s_mov_b64 s[10:11], s[18:19]
	s_lshl_b32 s6, s0, 3
	v_lshlrev_b32_e32 v134, 2, v2
	v_lshl_add_u64 v[2:3], s[10:11], 0, v[74:75]
	s_mov_b64 s[0:1], 0x4000
	v_lshl_add_u64 v[4:5], s[12:13], 0, v[74:75]
	v_lshl_add_u64 v[76:77], v[2:3], 0, s[0:1]
	v_lshl_add_u64 v[78:79], v[4:5], 0, s[0:1]
	v_lshlrev_b32_e32 v208, 4, v0
	v_add_u32_e32 v208, 0x4000, v208
	v_add_u32_e32 v209, 0x2000, v208
	global_load_dwordx4 v[212:215], v208, s[10:11]
	global_load_dwordx4 v[216:219], v209, s[10:11]
	global_load_dwordx4 v[220:223], v208, s[12:13]
	global_load_dwordx4 v[224:227], v209, s[12:13]
	v_add_u32_e32 v210, 0xe000, v208
	v_lshlrev_b32_e32 v228, 4, v178
	v_add_u32_e32 v228, 0x12000, v228
	s_waitcnt vmcnt(0)
	ds_write_b128 v210, v[212:215]
	ds_write_b128 v210, v[216:219] offset:8192
	ds_write_b128 v210, v[220:223] offset:16384
	ds_write_b128 v210, v[224:227] offset:24576
	s_waitcnt lgkmcnt(0)
	s_barrier
	s_mov_b64 s[0:1], 0x5000
	v_lshl_add_u64 v[80:81], v[2:3], 0, s[0:1]
	v_lshl_add_u64 v[82:83], v[4:5], 0, s[0:1]
	s_mov_b64 s[0:1], 0x5400
	v_lshl_add_u64 v[84:85], v[2:3], 0, s[0:1]
	v_lshl_add_u64 v[86:87], v[4:5], 0, s[0:1]
	s_mov_b64 s[0:1], 0x5800
	v_lshl_add_u64 v[88:89], v[2:3], 0, s[0:1]
	v_lshl_add_u64 v[90:91], v[4:5], 0, s[0:1]
	s_mov_b64 s[0:1], 0x5c00
	v_lshl_add_u64 v[92:93], v[2:3], 0, s[0:1]
	v_lshl_add_u64 v[94:95], v[4:5], 0, s[0:1]
	s_mov_b64 s[0:1], 0x6000
	v_lshl_add_u64 v[96:97], v[2:3], 0, s[0:1]
	v_lshl_add_u64 v[98:99], v[4:5], 0, s[0:1]
	s_mov_b64 s[0:1], 0x6400
	v_lshl_add_u64 v[100:101], v[2:3], 0, s[0:1]
	v_lshl_add_u64 v[102:103], v[4:5], 0, s[0:1]
	s_mov_b64 s[0:1], 0x6800
	v_lshl_add_u64 v[104:105], v[2:3], 0, s[0:1]
	v_lshl_add_u64 v[106:107], v[4:5], 0, s[0:1]
	s_mov_b64 s[0:1], 0x6c00
	v_lshl_add_u64 v[108:109], v[2:3], 0, s[0:1]
	v_lshl_add_u64 v[110:111], v[4:5], 0, s[0:1]
	s_mov_b64 s[0:1], 0x7000
	v_lshl_add_u64 v[112:113], v[2:3], 0, s[0:1]
	v_lshl_add_u64 v[114:115], v[4:5], 0, s[0:1]
	s_mov_b64 s[0:1], 0x7400
	v_lshl_add_u64 v[116:117], v[2:3], 0, s[0:1]
	v_lshl_add_u64 v[118:119], v[4:5], 0, s[0:1]
	s_mov_b64 s[0:1], 0x7800
	v_lshl_add_u64 v[120:121], v[2:3], 0, s[0:1]
	v_lshl_add_u64 v[122:123], v[4:5], 0, s[0:1]
	s_mov_b64 s[0:1], 0x7c00
	s_ashr_i32 s5, s4, 31
	v_lshl_add_u64 v[124:125], v[2:3], 0, s[0:1]
	v_lshl_add_u64 v[126:127], v[4:5], 0, s[0:1]
	s_lshl_b64 s[0:1], s[4:5], 14
	v_readlane_b32 s9, v249, 17
	s_add_u32 s8, s92, s0
	s_addc_u32 s9, s93, s1
	s_ashr_i32 s7, s6, 31
	s_mov_b64 s[14:15], s[22:23]
	s_lshl_b64 s[10:11], s[6:7], 14
	v_readlane_b32 s16, v249, 24
	v_readlane_b32 s17, v249, 25
	s_add_u32 s12, s14, s0
	v_lshlrev_b32_e32 v1, 2, v1
	s_addc_u32 s13, s15, s1
	s_mov_b32 s5, 0x53801000
	s_mov_b32 s7, 0x53802000
	s_mov_b32 s14, 0x53803000
	v_mov_b32_e32 v135, 0x3727c5ac
	s_mov_b32 s15, 0xf800000
	v_mov_b32_e32 v136, 0x260
	s_movk_i32 s16, 0x1000
	s_movk_i32 s17, 0x2000
	s_movk_i32 s18, 0x3000
.LBB0_1663:
	v_lshl_add_u64 v[50:51], s[8:9], 0, v[74:75]
	v_add_co_u32_e64 v2, s[0:1], s5, v50
	v_add_co_u32_e32 v52, vcc, 0x53800000, v50
	s_nop 0
	v_addc_co_u32_e64 v3, s[0:1], 0, v51, s[0:1]
	v_add_co_u32_e64 v4, s[0:1], s7, v50
	v_addc_co_u32_e32 v53, vcc, 0, v51, vcc
	s_nop 0
	v_addc_co_u32_e64 v5, s[0:1], 0, v51, s[0:1]
	v_add_co_u32_e64 v62, s[0:1], s14, v50
	ds_read_b128 v[54:57], v228
	ds_read_b128 v[58:61], v228 offset:16384
	v_addc_co_u32_e64 v63, s[0:1], 0, v51, s[0:1]
	global_load_dwordx4 v[46:49], v[4:5], off offset:-4096
	global_load_dwordx4 v[42:45], v[2:3], off offset:1024
	global_load_dwordx4 v[38:41], v[2:3], off offset:2048
	global_load_dwordx4 v[34:37], v[2:3], off offset:3072
	global_load_dwordx4 v[30:33], v[4:5], off
	global_load_dwordx4 v[26:29], v[4:5], off offset:1024
	global_load_dwordx4 v[22:25], v[4:5], off offset:2048
	global_load_dwordx4 v[18:21], v[4:5], off offset:3072
	global_load_dwordx4 v[14:17], v[62:63], off
	global_load_dwordx4 v[10:13], v[62:63], off offset:1024
	global_load_dwordx4 v[6:9], v[62:63], off offset:2048
	s_nop 0
	global_load_dwordx4 v[2:5], v[62:63], off offset:3072
	global_load_dwordx4 v[70:73], v[52:53], off
	global_load_dwordx4 v[66:69], v[52:53], off offset:1024
	s_nop 0
	global_load_dwordx4 v[62:65], v[52:53], off offset:2048
	s_nop 0
	global_load_dwordx4 v[50:53], v[52:53], off offset:3072
	v_lshl_add_u64 v[128:129], s[12:13], 0, v[74:75]
	s_add_i32 s4, s4, s6
	s_add_u32 s8, s8, s10
	s_addc_u32 s9, s9, s11
	s_add_u32 s12, s12, s10
	s_addc_u32 s13, s13, s11
	s_cmpk_lt_i32 s4, 0x2000
	s_waitcnt vmcnt(0)
	s_waitcnt lgkmcnt(0)
	v_mov_b32_e32 v138, v47
	v_mov_b32_e32 v139, v48
	v_mov_b32_e32 v140, v46
	v_mov_b32_e32 v141, v49
	v_add_f32_e32 v142, v42, v43
	v_add_f32_e32 v144, v44, v45
	v_mov_b32_e32 v143, v40
	v_mov_b32_e32 v145, v41
	v_mov_b32_e32 v146, v35
	v_mov_b32_e32 v147, v36
	v_mov_b32_e32 v148, v34
	v_mov_b32_e32 v149, v37
	v_mov_b32_e32 v154, v23
	v_mov_b32_e32 v155, v24
	v_mov_b32_e32 v156, v22
	v_mov_b32_e32 v157, v25
	v_mov_b32_e32 v170, v71
	v_mov_b32_e32 v171, v72
	v_mov_b32_e32 v172, v70
	v_mov_b32_e32 v173, v73
	v_mov_b32_e32 v174, v67
	v_mov_b32_e32 v175, v68
	v_mov_b32_e32 v176, v66
	v_mov_b32_e32 v177, v69
	v_pk_add_f32 v[138:139], v[138:139], v[140:141]
	v_pk_add_f32 v[140:141], v[142:143], v[144:145]
	v_pk_add_f32 v[142:143], v[146:147], v[148:149]
	v_pk_add_f32 v[146:147], v[154:155], v[156:157]
	v_pk_add_f32 v[154:155], v[170:171], v[172:173]
	v_pk_add_f32 v[156:157], v[174:175], v[176:177]
	v_add_f32_e32 v137, v154, v155
	v_pk_add_f32 v[154:155], v[156:157], v[156:157] op_sel:[0,1] op_sel_hi:[1,0]
	v_add_f32_e32 v158, v18, v19
	v_add_f32_e32 v160, v20, v21
	v_mov_b32_e32 v159, v16
	v_mov_b32_e32 v161, v17
	v_add_f32_e32 v178, v62, v63
	v_add_f32_e32 v180, v64, v65
	v_mov_b32_e32 v183, v50
	v_mov_b32_e32 v179, v52
	v_mov_b32_e32 v181, v53
	v_add_f32_e32 v182, 0, v137
	v_mov_b32_e32 v155, v51
	v_pk_add_f32 v[148:149], v[158:159], v[160:161]
	v_pk_add_f32 v[158:159], v[178:179], v[180:181]
	v_pk_add_f32 v[154:155], v[182:183], v[154:155]
	v_pk_add_f32 v[138:139], v[138:139], v[138:139] op_sel:[0,1] op_sel_hi:[1,0]
	v_pk_add_f32 v[154:155], v[154:155], v[158:159]
	v_mov_b32_e32 v139, v39
	v_pk_add_f32 v[154:155], v[154:155], v[154:155] op_sel:[0,1] op_sel_hi:[1,0]
	v_pk_add_f32 v[142:143], v[142:143], v[142:143] op_sel:[0,1] op_sel_hi:[1,0]
	v_mov_b32_e32 v155, v38
	v_pk_add_f32 v[138:139], v[154:155], v[138:139]
	v_add_f32_e32 v150, v30, v31
	v_pk_add_f32 v[138:139], v[138:139], v[140:141]
	v_add_f32_e32 v152, v32, v33
	v_pk_add_f32 v[138:139], v[138:139], v[138:139] op_sel:[0,1] op_sel_hi:[1,0]
	v_mov_b32_e32 v151, v28
	v_mov_b32_e32 v153, v29
	v_mov_b32_e32 v143, v27
	v_mov_b32_e32 v139, v26
	v_pk_add_f32 v[144:145], v[150:151], v[152:153]
	v_pk_add_f32 v[138:139], v[138:139], v[142:143]
	v_pk_add_f32 v[146:147], v[146:147], v[146:147] op_sel:[0,1] op_sel_hi:[1,0]
	v_pk_add_f32 v[138:139], v[138:139], v[144:145]
	v_mov_b32_e32 v147, v15
	v_pk_add_f32 v[138:139], v[138:139], v[138:139] op_sel:[0,1] op_sel_hi:[1,0]
	v_mov_b32_e32 v162, v11
	v_mov_b32_e32 v139, v14
	v_mov_b32_e32 v163, v12
	v_mov_b32_e32 v164, v10
	v_mov_b32_e32 v165, v13
	v_pk_add_f32 v[138:139], v[138:139], v[146:147]
	v_pk_add_f32 v[150:151], v[162:163], v[164:165]
	v_pk_add_f32 v[138:139], v[138:139], v[148:149]
	v_pk_add_f32 v[150:151], v[150:151], v[150:151] op_sel:[0,1] op_sel_hi:[1,0]
	v_pk_add_f32 v[138:139], v[138:139], v[138:139] op_sel:[0,1] op_sel_hi:[1,0]
	v_add_f32_e32 v166, v6, v7
	v_add_f32_e32 v168, v8, v9
	v_mov_b32_e32 v167, v4
	v_mov_b32_e32 v169, v5
	v_mov_b32_e32 v151, v3
	v_mov_b32_e32 v139, v2
	v_pk_add_f32 v[152:153], v[166:167], v[168:169]
	v_pk_add_f32 v[138:139], v[138:139], v[150:151]
	s_nop 0
	v_pk_add_f32 v[138:139], v[138:139], v[152:153]
	s_nop 0
	v_add_f32_e32 v137, v138, v139
	ds_bpermute_b32 v138, v1, v137
	s_waitcnt lgkmcnt(0)
	v_add_f32_e32 v137, v137, v138
	ds_bpermute_b32 v138, v130, v137
	s_waitcnt lgkmcnt(0)
	v_add_f32_e32 v137, v137, v138
	ds_bpermute_b32 v138, v131, v137
	s_waitcnt lgkmcnt(0)
	v_add_f32_e32 v137, v137, v138
	ds_bpermute_b32 v138, v132, v137
	s_waitcnt lgkmcnt(0)
	v_add_f32_e32 v137, v137, v138
	ds_bpermute_b32 v138, v133, v137
	s_waitcnt lgkmcnt(0)
	v_add_f32_e32 v137, v137, v138
	ds_bpermute_b32 v138, v134, v137
	s_waitcnt lgkmcnt(0)
	v_add_f32_e32 v137, v137, v138
	v_fmamk_f32 v71, v137, 0xb9800000, v71
	v_fmamk_f32 v70, v137, 0xb9800000, v70
	v_fmamk_f32 v73, v137, 0xb9800000, v73
	v_fmac_f32_e32 v72, 0xb9800000, v137
	v_fmamk_f32 v67, v137, 0xb9800000, v67
	v_fmamk_f32 v66, v137, 0xb9800000, v66
	v_fmamk_f32 v69, v137, 0xb9800000, v69
	v_fmac_f32_e32 v68, 0xb9800000, v137
	v_fmamk_f32 v139, v137, 0xb9800000, v53
	v_fmamk_f32 v138, v137, 0xb9800000, v52
	v_fmamk_f32 v53, v137, 0xb9800000, v47
	v_fmamk_f32 v52, v137, 0xb9800000, v46
	v_fmamk_f32 v47, v137, 0xb9800000, v43
	v_fmamk_f32 v46, v137, 0xb9800000, v42
	v_fmamk_f32 v43, v137, 0xb9800000, v41
	v_fmamk_f32 v42, v137, 0xb9800000, v40
	v_pk_mul_f32 v[40:41], v[72:73], v[72:73]
	v_pk_mul_f32 v[140:141], v[70:71], v[70:71]
	v_pk_mul_f32 v[142:143], v[68:69], v[68:69]
	v_pk_mul_f32 v[144:145], v[66:67], v[66:67]
	v_fmamk_f32 v62, v137, 0xb9800000, v62
	v_fmac_f32_e32 v64, 0xb9800000, v137
	v_pk_mov_b32 v[182:183], v[140:141], v[40:41] op_sel:[1,0]
	v_mov_b32_e32 v141, v41
	v_pk_mov_b32 v[40:41], v[144:145], v[142:143] op_sel:[1,0]
	v_mov_b32_e32 v145, v143
	v_fmamk_f32 v63, v137, 0xb9800000, v63
	v_fmamk_f32 v65, v137, 0xb9800000, v65
	v_mul_f32_e32 v146, v62, v62
	v_mul_f32_e32 v148, v64, v64
	v_pk_add_f32 v[140:141], v[182:183], v[140:141]
	v_pk_add_f32 v[40:41], v[40:41], v[144:145]
	v_fmamk_f32 v51, v137, 0xb9800000, v51
	v_fmac_f32_e32 v50, 0xb9800000, v137
	v_fmamk_f32 v49, v137, 0xb9800000, v49
	v_fmac_f32_e32 v48, 0xb9800000, v137
	v_pk_fma_f32 v[142:143], v[62:63], v[62:63], v[146:147] op_sel_hi:[1,1,0]
	v_pk_fma_f32 v[146:147], v[64:65], v[64:65], v[148:149] op_sel_hi:[1,1,0]
	v_pk_add_f32 v[140:141], v[140:141], v[140:141] op_sel_hi:[0,1]
	v_pk_add_f32 v[40:41], v[40:41], v[40:41] op_sel_hi:[0,1]
	v_pk_mul_f32 v[150:151], v[48:49], v[48:49]
	v_pk_mul_f32 v[152:153], v[52:53], v[52:53]
	v_mul_f32_e32 v142, v50, v50
	v_mul_f32_e32 v146, v51, v51
	v_mul_f32_e32 v140, v138, v138
	v_mul_f32_e32 v40, v139, v139
	v_fmac_f32_e32 v44, 0xb9800000, v137
	v_pk_mov_b32 v[148:149], v[152:153], v[150:151] op_sel:[1,0]
	v_mov_b32_e32 v153, v151
	v_pk_add_f32 v[142:143], v[142:143], v[146:147]
	v_pk_add_f32 v[40:41], v[140:141], v[40:41]
	v_fmamk_f32 v45, v137, 0xb9800000, v45
	v_mul_f32_e32 v154, v46, v46
	v_mul_f32_e32 v156, v44, v44
	v_pk_add_f32 v[144:145], v[148:149], v[152:153]
	v_pk_add_f32 v[40:41], v[142:143], v[40:41]
	v_fmamk_f32 v39, v137, 0xb9800000, v39
	v_fmac_f32_e32 v38, 0xb9800000, v137
	v_fmamk_f32 v35, v137, 0xb9800000, v35
	v_fmamk_f32 v34, v137, 0xb9800000, v34
	v_fmamk_f32 v37, v137, 0xb9800000, v37
	v_fmac_f32_e32 v36, 0xb9800000, v137
	v_pk_fma_f32 v[150:151], v[46:47], v[46:47], v[154:155] op_sel_hi:[1,1,0]
	v_pk_fma_f32 v[154:155], v[44:45], v[44:45], v[156:157] op_sel_hi:[1,1,0]
	v_pk_add_f32 v[144:145], v[144:145], v[144:145] op_sel_hi:[0,1]
	v_pk_add_f32 v[40:41], v[40:41], v[40:41] op_sel_hi:[0,1]
	v_pk_mul_f32 v[158:159], v[36:37], v[36:37]
	v_pk_mul_f32 v[160:161], v[34:35], v[34:35]
	v_mul_f32_e32 v150, v38, v38
	v_mul_f32_e32 v154, v39, v39
	v_mul_f32_e32 v144, v42, v42
	v_mul_f32_e32 v40, v43, v43
	v_fmamk_f32 v30, v137, 0xb9800000, v30
	v_fmac_f32_e32 v32, 0xb9800000, v137
	v_pk_mov_b32 v[156:157], v[160:161], v[158:159] op_sel:[1,0]
	v_mov_b32_e32 v161, v159
	v_pk_add_f32 v[146:147], v[150:151], v[154:155]
	v_pk_add_f32 v[40:41], v[144:145], v[40:41]
	v_fmamk_f32 v31, v137, 0xb9800000, v31
	v_fmamk_f32 v33, v137, 0xb9800000, v33
	v_mul_f32_e32 v162, v30, v30
	v_mul_f32_e32 v164, v32, v32
	v_pk_add_f32 v[148:149], v[156:157], v[160:161]
	v_pk_add_f32 v[40:41], v[146:147], v[40:41]
	v_fmamk_f32 v29, v137, 0xb9800000, v29
	v_fmamk_f32 v28, v137, 0xb9800000, v28
	v_fmamk_f32 v27, v137, 0xb9800000, v27
	v_fmac_f32_e32 v26, 0xb9800000, v137
	v_fmamk_f32 v23, v137, 0xb9800000, v23
	v_fmamk_f32 v22, v137, 0xb9800000, v22
	v_fmamk_f32 v25, v137, 0xb9800000, v25
	v_fmac_f32_e32 v24, 0xb9800000, v137
	v_pk_fma_f32 v[158:159], v[30:31], v[30:31], v[162:163] op_sel_hi:[1,1,0]
	v_pk_fma_f32 v[162:163], v[32:33], v[32:33], v[164:165] op_sel_hi:[1,1,0]
	v_pk_add_f32 v[148:149], v[148:149], v[148:149] op_sel_hi:[0,1]
	v_pk_add_f32 v[40:41], v[40:41], v[40:41] op_sel_hi:[0,1]
	v_pk_mul_f32 v[166:167], v[24:25], v[24:25]
	v_pk_mul_f32 v[168:169], v[22:23], v[22:23]
	v_mul_f32_e32 v158, v26, v26
	v_mul_f32_e32 v162, v27, v27
	v_mul_f32_e32 v148, v28, v28
	v_mul_f32_e32 v40, v29, v29
	v_fmamk_f32 v18, v137, 0xb9800000, v18
	v_fmac_f32_e32 v20, 0xb9800000, v137
	v_pk_mov_b32 v[164:165], v[168:169], v[166:167] op_sel:[1,0]
	v_mov_b32_e32 v169, v167
	v_pk_add_f32 v[150:151], v[158:159], v[162:163]
	v_pk_add_f32 v[40:41], v[148:149], v[40:41]
	v_fmamk_f32 v19, v137, 0xb9800000, v19
	v_fmamk_f32 v21, v137, 0xb9800000, v21
	v_mul_f32_e32 v170, v18, v18
	v_mul_f32_e32 v172, v20, v20
	v_pk_add_f32 v[152:153], v[164:165], v[168:169]
	v_pk_add_f32 v[40:41], v[150:151], v[40:41]
	v_fmamk_f32 v17, v137, 0xb9800000, v17
	v_fmamk_f32 v16, v137, 0xb9800000, v16
	v_fmamk_f32 v15, v137, 0xb9800000, v15
	v_fmac_f32_e32 v14, 0xb9800000, v137
	v_fmamk_f32 v11, v137, 0xb9800000, v11
	v_fmamk_f32 v10, v137, 0xb9800000, v10
	v_fmamk_f32 v13, v137, 0xb9800000, v13
	v_fmac_f32_e32 v12, 0xb9800000, v137
	v_pk_fma_f32 v[166:167], v[18:19], v[18:19], v[170:171] op_sel_hi:[1,1,0]
	v_pk_fma_f32 v[170:171], v[20:21], v[20:21], v[172:173] op_sel_hi:[1,1,0]
	v_pk_add_f32 v[152:153], v[152:153], v[152:153] op_sel_hi:[0,1]
	v_pk_add_f32 v[40:41], v[40:41], v[40:41] op_sel_hi:[0,1]
	v_pk_mul_f32 v[174:175], v[12:13], v[12:13]
	v_pk_mul_f32 v[176:177], v[10:11], v[10:11]
	v_mul_f32_e32 v166, v14, v14
	v_mul_f32_e32 v170, v15, v15
	v_mul_f32_e32 v152, v16, v16
	v_mul_f32_e32 v40, v17, v17
	v_fmamk_f32 v6, v137, 0xb9800000, v6
	v_fmac_f32_e32 v8, 0xb9800000, v137
	v_pk_mov_b32 v[172:173], v[176:177], v[174:175] op_sel:[1,0]
	v_mov_b32_e32 v177, v175
	v_pk_add_f32 v[154:155], v[166:167], v[170:171]
	v_pk_add_f32 v[40:41], v[152:153], v[40:41]
	v_fmamk_f32 v7, v137, 0xb9800000, v7
	v_fmamk_f32 v9, v137, 0xb9800000, v9
	v_mul_f32_e32 v178, v6, v6
	v_mul_f32_e32 v180, v8, v8
	v_pk_add_f32 v[156:157], v[172:173], v[176:177]
	v_pk_add_f32 v[40:41], v[154:155], v[40:41]
	v_fmamk_f32 v5, v137, 0xb9800000, v5
	v_fmamk_f32 v4, v137, 0xb9800000, v4
	v_fmamk_f32 v3, v137, 0xb9800000, v3
	v_fmac_f32_e32 v2, 0xb9800000, v137
	v_pk_fma_f32 v[174:175], v[6:7], v[6:7], v[178:179] op_sel_hi:[1,1,0]
	v_pk_fma_f32 v[178:179], v[8:9], v[8:9], v[180:181] op_sel_hi:[1,1,0]
	v_pk_add_f32 v[156:157], v[156:157], v[156:157] op_sel_hi:[0,1]
	v_pk_add_f32 v[40:41], v[40:41], v[40:41] op_sel_hi:[0,1]
	v_mul_f32_e32 v174, v2, v2
	v_mul_f32_e32 v178, v3, v3
	v_mul_f32_e32 v156, v4, v4
	v_mul_f32_e32 v40, v5, v5
	v_pk_add_f32 v[158:159], v[174:175], v[178:179]
	v_pk_add_f32 v[40:41], v[156:157], v[40:41]
	s_nop 0
	v_pk_add_f32 v[40:41], v[158:159], v[40:41]
	s_nop 0
	v_add_f32_e32 v40, v40, v41
	ds_bpermute_b32 v41, v1, v40
	s_waitcnt lgkmcnt(0)
	v_add_f32_e32 v40, v40, v41
	ds_bpermute_b32 v41, v130, v40
	s_waitcnt lgkmcnt(0)
	v_add_f32_e32 v40, v40, v41
	ds_bpermute_b32 v41, v131, v40
	s_waitcnt lgkmcnt(0)
	v_add_f32_e32 v40, v40, v41
	ds_bpermute_b32 v41, v132, v40
	s_waitcnt lgkmcnt(0)
	v_add_f32_e32 v40, v40, v41
	ds_bpermute_b32 v41, v133, v40
	s_waitcnt lgkmcnt(0)
	v_add_f32_e32 v40, v40, v41
	ds_bpermute_b32 v41, v134, v40
	s_waitcnt lgkmcnt(0)
	v_add_f32_e32 v40, v40, v41
	v_fmamk_f32 v40, v40, 0x39800000, v135
	v_mul_f32_e32 v41, 0x4f800000, v40
	v_cmp_gt_f32_e32 vcc, s15, v40
	s_nop 1
	v_cndmask_b32_e32 v40, v40, v41, vcc
	v_sqrt_f32_e32 v41, v40
	s_nop 0
	v_add_u32_e32 v137, -1, v41
	v_add_u32_e32 v140, 1, v41
	v_fma_f32 v141, -v137, v41, v40
	v_fma_f32 v142, -v140, v41, v40
	v_cmp_ge_f32_e64 s[0:1], 0, v141
	s_nop 1
	v_cndmask_b32_e64 v41, v41, v137, s[0:1]
	v_cmp_lt_f32_e64 s[0:1], 0, v142
	s_nop 1
	v_cndmask_b32_e64 v41, v41, v140, s[0:1]
	v_mul_f32_e32 v137, 0x37800000, v41
	v_cndmask_b32_e32 v41, v41, v137, vcc
	v_cmp_class_f32_e32 vcc, v40, v136
	s_nop 1
	v_cndmask_b32_e32 v40, v41, v40, vcc
	v_div_scale_f32 v41, s[0:1], v40, v40, 1.0
	v_rcp_f32_e32 v140, v41
	v_div_scale_f32 v137, vcc, 1.0, v40, 1.0
	v_fma_f32 v141, -v41, v140, 1.0
	v_fmac_f32_e32 v140, v141, v140
	v_mul_f32_e32 v141, v137, v140
	v_fma_f32 v142, -v41, v141, v137
	v_fmac_f32_e32 v141, v142, v140
	v_fma_f32 v41, -v41, v141, v137
	v_div_fmas_f32 v41, v41, v140, v141
	v_div_fixup_f32 v40, v41, v40, 1.0
	v_pk_mul_f32 v[70:71], v[70:71], v[40:41] op_sel_hi:[1,0]
	v_pk_mul_f32 v[72:73], v[72:73], v[40:41] op_sel_hi:[1,0]
	v_pk_fma_f32 v[54:55], v[54:55], v[70:71], v[58:59]
	v_pk_fma_f32 v[56:57], v[56:57], v[72:73], v[60:61]
	global_store_dwordx4 v[128:129], v[54:57], off
	ds_read_b128 v[54:57], v228 offset:1024
	s_nop 0
	ds_read_b128 v[58:61], v228 offset:17408
	v_pk_mul_f32 v[68:69], v[68:69], v[40:41] op_sel_hi:[1,0]
	v_pk_mul_f32 v[66:67], v[66:67], v[40:41] op_sel_hi:[1,0]
	v_pk_mul_f32 v[64:65], v[64:65], v[40:41] op_sel_hi:[1,0]
	v_pk_mul_f32 v[62:63], v[62:63], v[40:41] op_sel_hi:[1,0]
	v_pk_mul_f32 v[50:51], v[50:51], v[40:41] op_sel_hi:[1,0]
	v_pk_mul_f32 v[38:39], v[38:39], v[40:41] op_sel_hi:[1,0]
	v_pk_mul_f32 v[36:37], v[36:37], v[40:41] op_sel_hi:[1,0]
	v_pk_mul_f32 v[34:35], v[34:35], v[40:41] op_sel_hi:[1,0]
	v_pk_mul_f32 v[32:33], v[32:33], v[40:41] op_sel_hi:[1,0]
	v_pk_mul_f32 v[30:31], v[30:31], v[40:41] op_sel_hi:[1,0]
	v_pk_mul_f32 v[28:29], v[28:29], v[40:41] op_sel_hi:[1,0]
	v_pk_mul_f32 v[26:27], v[26:27], v[40:41] op_sel_hi:[1,0]
	v_pk_mul_f32 v[24:25], v[24:25], v[40:41] op_sel_hi:[1,0]
	v_pk_mul_f32 v[22:23], v[22:23], v[40:41] op_sel_hi:[1,0]
	v_pk_mul_f32 v[20:21], v[20:21], v[40:41] op_sel_hi:[1,0]
	v_pk_mul_f32 v[18:19], v[18:19], v[40:41] op_sel_hi:[1,0]
	v_pk_mul_f32 v[16:17], v[16:17], v[40:41] op_sel_hi:[1,0]
	v_pk_mul_f32 v[14:15], v[14:15], v[40:41] op_sel_hi:[1,0]
	v_pk_mul_f32 v[12:13], v[12:13], v[40:41] op_sel_hi:[1,0]
	v_pk_mul_f32 v[10:11], v[10:11], v[40:41] op_sel_hi:[1,0]
	v_pk_mul_f32 v[8:9], v[8:9], v[40:41] op_sel_hi:[1,0]
	v_pk_mul_f32 v[6:7], v[6:7], v[40:41] op_sel_hi:[1,0]
	v_pk_mul_f32 v[4:5], v[4:5], v[40:41] op_sel_hi:[1,0]
	v_pk_mul_f32 v[2:3], v[2:3], v[40:41] op_sel_hi:[1,0]
	s_waitcnt lgkmcnt(0)
	v_pk_fma_f32 v[54:55], v[54:55], v[66:67], v[58:59]
	v_pk_fma_f32 v[56:57], v[56:57], v[68:69], v[60:61]
	global_store_dwordx4 v[128:129], v[54:57], off offset:1024
	ds_read_b128 v[54:57], v228 offset:2048
	s_nop 0
	ds_read_b128 v[58:61], v228 offset:18432
	s_waitcnt lgkmcnt(0)
	v_pk_fma_f32 v[54:55], v[54:55], v[62:63], v[58:59]
	v_pk_fma_f32 v[56:57], v[56:57], v[64:65], v[60:61]
	global_store_dwordx4 v[128:129], v[54:57], off offset:2048
	ds_read_b128 v[54:57], v228 offset:3072
	s_nop 0
	ds_read_b128 v[58:61], v228 offset:19456
	v_pk_mul_f32 v[62:63], v[138:139], v[40:41] op_sel_hi:[1,0]
	s_waitcnt lgkmcnt(0)
	v_pk_fma_f32 v[54:55], v[54:55], v[50:51], v[58:59]
	v_pk_fma_f32 v[56:57], v[56:57], v[62:63], v[60:61]
	global_store_dwordx4 v[128:129], v[54:57], off offset:3072
	ds_read_b128 v[54:57], v228 offset:4096
	s_nop 0
	ds_read_b128 v[58:61], v228 offset:20480
	v_add_co_u32_e32 v62, vcc, s17, v128
	v_pk_mul_f32 v[50:51], v[48:49], v[40:41] op_sel_hi:[1,0]
	v_pk_mul_f32 v[48:49], v[52:53], v[40:41] op_sel_hi:[1,0]
	v_addc_co_u32_e32 v63, vcc, 0, v129, vcc
	s_waitcnt lgkmcnt(0)
	v_pk_fma_f32 v[48:49], v[54:55], v[48:49], v[58:59]
	v_pk_fma_f32 v[50:51], v[56:57], v[50:51], v[60:61]
	global_store_dwordx4 v[62:63], v[48:51], off offset:-4096
	ds_read_b128 v[48:51], v228 offset:5120
	s_nop 0
	ds_read_b128 v[52:55], v228 offset:21504
	v_add_co_u32_e32 v56, vcc, s16, v128
	v_pk_mul_f32 v[58:59], v[44:45], v[40:41] op_sel_hi:[1,0]
	v_pk_mul_f32 v[44:45], v[46:47], v[40:41] op_sel_hi:[1,0]
	v_addc_co_u32_e32 v57, vcc, 0, v129, vcc
	s_waitcnt lgkmcnt(0)
	v_pk_fma_f32 v[44:45], v[48:49], v[44:45], v[52:53]
	v_pk_fma_f32 v[46:47], v[50:51], v[58:59], v[54:55]
	global_store_dwordx4 v[56:57], v[44:47], off offset:1024
	ds_read_b128 v[44:47], v228 offset:6144
	s_nop 0
	ds_read_b128 v[48:51], v228 offset:22528
	v_pk_mul_f32 v[52:53], v[42:43], v[40:41] op_sel_hi:[1,0]
	s_waitcnt lgkmcnt(0)
	v_pk_fma_f32 v[42:43], v[44:45], v[38:39], v[48:49]
	v_pk_fma_f32 v[44:45], v[46:47], v[52:53], v[50:51]
	global_store_dwordx4 v[56:57], v[42:45], off offset:2048
	ds_read_b128 v[42:45], v228 offset:7168
	s_nop 0
	ds_read_b128 v[46:49], v228 offset:23552
	s_waitcnt lgkmcnt(0)
	v_pk_fma_f32 v[34:35], v[42:43], v[34:35], v[46:47]
	v_pk_fma_f32 v[36:37], v[44:45], v[36:37], v[48:49]
	global_store_dwordx4 v[56:57], v[34:37], off offset:3072
	ds_read_b128 v[34:37], v228 offset:8192
	s_nop 0
	ds_read_b128 v[42:45], v228 offset:24576
	s_waitcnt lgkmcnt(0)
	v_pk_fma_f32 v[30:31], v[34:35], v[30:31], v[42:43]
	v_pk_fma_f32 v[32:33], v[36:37], v[32:33], v[44:45]
	global_store_dwordx4 v[62:63], v[30:33], off
	ds_read_b128 v[30:33], v228 offset:9216
	s_nop 0
	ds_read_b128 v[34:37], v228 offset:25600
	s_waitcnt lgkmcnt(0)
	v_pk_fma_f32 v[26:27], v[30:31], v[26:27], v[34:35]
	v_pk_fma_f32 v[28:29], v[32:33], v[28:29], v[36:37]
	global_store_dwordx4 v[62:63], v[26:29], off offset:1024
	ds_read_b128 v[26:29], v228 offset:10240
	s_nop 0
	ds_read_b128 v[30:33], v228 offset:26624
	s_waitcnt lgkmcnt(0)
	v_pk_fma_f32 v[22:23], v[26:27], v[22:23], v[30:31]
	v_pk_fma_f32 v[24:25], v[28:29], v[24:25], v[32:33]
	global_store_dwordx4 v[62:63], v[22:25], off offset:2048
	ds_read_b128 v[22:25], v228 offset:11264
	s_nop 0
	ds_read_b128 v[26:29], v228 offset:27648
	s_waitcnt lgkmcnt(0)
	v_pk_fma_f32 v[18:19], v[22:23], v[18:19], v[26:27]
	v_pk_fma_f32 v[20:21], v[24:25], v[20:21], v[28:29]
	global_store_dwordx4 v[62:63], v[18:21], off offset:3072
	ds_read_b128 v[18:21], v228 offset:12288
	s_nop 0
	ds_read_b128 v[22:25], v228 offset:28672
	v_add_co_u32_e32 v26, vcc, s18, v128
	s_waitcnt lgkmcnt(0)
	v_pk_fma_f32 v[14:15], v[14:15], v[18:19], v[22:23]
	v_addc_co_u32_e32 v27, vcc, 0, v129, vcc
	v_pk_fma_f32 v[16:17], v[16:17], v[20:21], v[24:25]
	global_store_dwordx4 v[26:27], v[14:17], off
	ds_read_b128 v[14:17], v228 offset:13312
	s_nop 0
	ds_read_b128 v[18:21], v228 offset:29696
	s_waitcnt lgkmcnt(0)
	v_pk_fma_f32 v[10:11], v[10:11], v[14:15], v[18:19]
	v_pk_fma_f32 v[12:13], v[12:13], v[16:17], v[20:21]
	global_store_dwordx4 v[26:27], v[10:13], off offset:1024
	ds_read_b128 v[10:13], v228 offset:14336
	s_nop 0
	ds_read_b128 v[14:17], v228 offset:30720
	s_waitcnt lgkmcnt(0)
	v_pk_fma_f32 v[6:7], v[6:7], v[10:11], v[14:15]
	v_pk_fma_f32 v[8:9], v[8:9], v[12:13], v[16:17]
	global_store_dwordx4 v[26:27], v[6:9], off offset:2048
	ds_read_b128 v[6:9], v228 offset:15360
	s_nop 0
	ds_read_b128 v[10:13], v228 offset:31744
	s_waitcnt lgkmcnt(0)
	v_pk_fma_f32 v[2:3], v[2:3], v[6:7], v[10:11]
	v_pk_fma_f32 v[4:5], v[4:5], v[8:9], v[12:13]
	global_store_dwordx4 v[26:27], v[2:5], off offset:3072
	s_cbranch_scc1 .LBB0_1663
